# quarter-unit K loop: MFMAs split 4/4/2/6 over the four barrier phases, the last six interleaved with the LDS-DMA loads of the refill phase
# baseline (speedup 1.0000x reference)
.Lq5_top:
	ds_read_b128 v[148:151], v214
	ds_read_b128 v[152:155], v214 offset:1024
	ds_read_b128 v[156:159], v214 offset:2048
	ds_read_b128 v[160:163], v214 offset:3072
	v_lshl_add_u64 v[2:3], s[34:35], 0, v[200:201]
	s_add_i32 m0, s48, 0xc000
	ds_read_b128 v[188:191], v216
	ds_read_b128 v[192:195], v216 offset:1024
	ds_read_b128 v[180:183], v216 offset:2048
	ds_read_b128 v[184:187], v216 offset:3072
	ds_read_b128 v[172:175], v216 offset:4096
	ds_read_b128 v[176:179], v216 offset:5120
	ds_read_b128 v[164:167], v216 offset:6144
	ds_read_b128 v[168:171], v216 offset:7168
	v_lshl_add_u64 v[2:3], s[34:35], 0, v[202:203]
	s_add_i32 m0, s48, 0xe000
	s_nop 0
	s_setprio 1
	v_mfma_f32_16x16x32_bf16 v[128:131], v[4:7], v[44:47], v[128:131]
	v_mfma_f32_16x16x32_bf16 v[124:127], v[12:15], v[44:47], v[124:127]
	v_mfma_f32_16x16x32_bf16 v[120:123], v[4:7], v[36:39], v[120:123]
	v_mfma_f32_16x16x32_bf16 v[116:119], v[12:15], v[36:39], v[116:119]
	s_setprio 0
	s_barrier
	v_cmp_ne_u32_e64 s[2:3], 1, v217
	s_andn2_b64 vcc, exec, s[26:27]
	s_add_u32 s56, s34, 0xfff80080
	s_addc_u32 s57, s35, -1
	s_cmp_eq_u32 s77, 12
	s_cselect_b32 s59, s39, s57
	s_cselect_b32 s58, s38, s56
	s_cselect_b32 s57, s47, s41
	s_cselect_b32 s56, s46, s18
	s_setprio 1
	v_mfma_f32_16x16x32_bf16 v[104:107], v[4:7], v[28:31], v[104:107]
	v_mfma_f32_16x16x32_bf16 v[100:103], v[12:15], v[28:31], v[100:103]
	v_mfma_f32_16x16x32_bf16 v[88:91], v[4:7], v[20:23], v[88:91]
	v_mfma_f32_16x16x32_bf16 v[84:87], v[12:15], v[20:23], v[84:87]
	s_setprio 0
	s_waitcnt lgkmcnt(0)
	s_barrier
	s_setprio 1
	v_mfma_f32_16x16x32_bf16 v[128:131], v[8:11], v[48:51], v[128:131]
	v_mfma_f32_16x16x32_bf16 v[124:127], v[16:19], v[48:51], v[124:127]
	s_setprio 0
	s_waitcnt vmcnt(0)
	s_barrier
	v_mfma_f32_16x16x32_bf16 v[120:123], v[8:11], v[40:43], v[120:123]
	v_mfma_f32_16x16x32_bf16 v[116:119], v[16:19], v[40:43], v[116:119]
	s_mov_b32 m0, s49
	v_lshl_add_u64 v[2:3], s[56:57], 0, v[198:199]
	s_add_u32 s78, s56, 0x80000
	global_load_lds_dwordx4 v[2:3], off
	v_mfma_f32_16x16x32_bf16 v[104:107], v[8:11], v[32:35], v[104:107]
	v_lshl_add_u64 v[204:205], s[56:57], 0, v[196:197]
	s_mov_b32 m0, s50
	s_addc_u32 s79, s57, 0
	global_load_lds_dwordx4 v[204:205], off
	v_mfma_f32_16x16x32_bf16 v[100:103], v[16:19], v[32:35], v[100:103]
	v_lshl_add_u64 v[206:207], s[78:79], 0, v[198:199]
	s_mov_b32 m0, s51
	v_lshl_add_u64 v[208:209], s[58:59], 0, v[196:197]
	v_lshl_add_u64 v[206:207], s[78:79], 0, v[196:197]
	s_mov_b32 m0, s60
	s_and_b64 vcc, exec, s[2:3]
	v_lshl_add_u64 v[206:207], s[58:59], 0, v[198:199]
	s_mov_b32 m0, s48
	s_nop 0
	global_load_lds_dwordx4 v[206:207], off
	v_mfma_f32_16x16x32_bf16 v[88:91], v[8:11], v[24:27], v[88:91]
	s_mov_b32 m0, s61
	s_nop 0
	global_load_lds_dwordx4 v[208:209], off
	v_mfma_f32_16x16x32_bf16 v[84:87], v[16:19], v[24:27], v[84:87]
	s_barrier
	v_add_u32_e32 v1, 0x18000, v213
	ds_read_b128 v[4:7], v1
	ds_read_b128 v[8:11], v1 offset:1024
	ds_read_b128 v[12:15], v1 offset:2048
	ds_read_b128 v[16:19], v1 offset:3072
	v_add_u32_e32 v1, 0x1c000, v213
	s_add_u32 s58, s58, 0x80000
	s_addc_u32 s59, s59, 0
	s_mov_b32 m0, s62
	v_lshl_add_u64 v[218:219], s[58:59], 0, v[198:199]
	ds_read_b128 v[44:47], v216 offset:32768
	ds_read_b128 v[48:51], v216 offset:33792
	ds_read_b128 v[36:39], v216 offset:34816
	ds_read_b128 v[40:43], v216 offset:35840
	ds_read_b128 v[28:31], v216 offset:36864
	ds_read_b128 v[32:35], v216 offset:37888
	ds_read_b128 v[20:23], v216 offset:38912
	ds_read_b128 v[24:27], v216 offset:39936
	v_lshl_add_u64 v[218:219], s[58:59], 0, v[196:197]
	s_mov_b32 m0, s63
	s_nop 0
	s_setprio 1
	v_mfma_f32_16x16x32_bf16 v[128:131], v[148:151], v[188:191], v[128:131]
	v_mfma_f32_16x16x32_bf16 v[124:127], v[156:159], v[188:191], v[124:127]
	v_mfma_f32_16x16x32_bf16 v[120:123], v[148:151], v[180:183], v[120:123]
	v_mfma_f32_16x16x32_bf16 v[116:119], v[156:159], v[180:183], v[116:119]
	s_setprio 0
	s_barrier
	s_and_b64 vcc, exec, s[2:3]
	s_setprio 1
	v_mfma_f32_16x16x32_bf16 v[104:107], v[148:151], v[172:175], v[104:107]
	v_mfma_f32_16x16x32_bf16 v[100:103], v[156:159], v[172:175], v[100:103]
	v_mfma_f32_16x16x32_bf16 v[88:91], v[148:151], v[164:167], v[88:91]
	v_mfma_f32_16x16x32_bf16 v[84:87], v[156:159], v[164:167], v[84:87]
	s_setprio 0
	s_waitcnt lgkmcnt(0)
	s_barrier
	s_setprio 1
	v_mfma_f32_16x16x32_bf16 v[128:131], v[152:155], v[192:195], v[128:131]
	v_mfma_f32_16x16x32_bf16 v[124:127], v[160:163], v[192:195], v[124:127]
	s_setprio 0
	s_waitcnt vmcnt(0)
	s_barrier
	v_mfma_f32_16x16x32_bf16 v[120:123], v[152:155], v[184:187], v[120:123]
	v_mfma_f32_16x16x32_bf16 v[116:119], v[160:163], v[184:187], v[116:119]
	s_mov_b32 m0, s66
	v_lshl_add_u64 v[2:3], v[2:3], 0, s[16:17]
	s_add_u32 s56, s56, 0x80080
	global_load_lds_dwordx4 v[2:3], off
	v_mfma_f32_16x16x32_bf16 v[104:107], v[152:155], v[176:179], v[104:107]
	v_lshl_add_u64 v[2:3], v[204:205], 0, s[16:17]
	s_mov_b32 m0, s67
	s_addc_u32 s57, s57, 0
	global_load_lds_dwordx4 v[2:3], off
	v_mfma_f32_16x16x32_bf16 v[100:103], v[160:163], v[176:179], v[100:103]
	v_lshl_add_u64 v[2:3], s[56:57], 0, v[198:199]
	s_mov_b32 m0, s70
	s_and_b64 vcc, exec, s[2:3]
	v_lshl_add_u64 v[2:3], s[56:57], 0, v[196:197]
	s_mov_b32 m0, s71
	s_nop 0
	v_lshl_add_u64 v[2:3], v[206:207], 0, s[16:17]
	s_mov_b32 m0, s68
	s_nop 0
	global_load_lds_dwordx4 v[2:3], off
	v_mfma_f32_16x16x32_bf16 v[88:91], v[152:155], v[168:171], v[88:91]
	v_lshl_add_u64 v[2:3], v[208:209], 0, s[16:17]
	s_mov_b32 m0, s69
	s_nop 0
	global_load_lds_dwordx4 v[2:3], off
	v_mfma_f32_16x16x32_bf16 v[84:87], v[160:163], v[168:171], v[84:87]
	s_branch .Lq5_be

.Lq6_top:
	ds_read_b128 v[180:183], v247
	ds_read_b128 v[184:187], v247 offset:1024
	ds_read_b128 v[188:191], v247 offset:2048
	ds_read_b128 v[192:195], v247 offset:3072
	v_lshl_add_u64 v[2:3], s[38:39], 0, v[232:233]
	s_add_i32 m0, s44, 0xc000
	ds_read_b128 v[220:223], v249
	ds_read_b128 v[224:227], v249 offset:1024
	ds_read_b128 v[212:215], v249 offset:2048
	ds_read_b128 v[216:219], v249 offset:3072
	ds_read_b128 v[204:207], v249 offset:4096
	ds_read_b128 v[208:211], v249 offset:5120
	ds_read_b128 v[196:199], v249 offset:6144
	ds_read_b128 v[200:203], v249 offset:7168
	v_lshl_add_u64 v[2:3], s[38:39], 0, v[234:235]
	s_add_i32 m0, s44, 0xe000
	s_nop 0
	s_setprio 1
	v_mfma_f32_16x16x32_bf16 v[68:71], v[4:7], v[44:47], v[160:163]
	v_mfma_f32_16x16x32_bf16 v[72:75], v[12:15], v[44:47], v[156:159]
	v_mfma_f32_16x16x32_bf16 v[76:79], v[4:7], v[36:39], v[152:155]
	v_mfma_f32_16x16x32_bf16 v[80:83], v[12:15], v[36:39], v[148:151]
	s_setprio 0
	s_barrier
	v_cmp_ne_u32_e64 s[4:5], 1, v251
	s_andn2_b64 vcc, exec, s[34:35]
	s_add_u32 s40, s38, 0xfff80080
	s_addc_u32 s41, s39, -1
	s_cmp_eq_u32 s84, 28
	s_cselect_b32 s47, s29, s41
	s_cselect_b32 s46, s28, s40
	s_cselect_b32 s41, s37, s27
	s_cselect_b32 s40, s36, s16
	s_setprio 1
	v_mfma_f32_16x16x32_bf16 v[84:87], v[4:7], v[28:31], v[136:139]
	v_mfma_f32_16x16x32_bf16 v[92:95], v[12:15], v[28:31], v[132:135]
	v_mfma_f32_16x16x32_bf16 v[96:99], v[4:7], v[20:23], v[120:123]
	v_mfma_f32_16x16x32_bf16 v[100:103], v[12:15], v[20:23], v[112:115]
	s_setprio 0
	s_waitcnt lgkmcnt(0)
	s_barrier
	s_setprio 1
	v_mfma_f32_16x16x32_bf16 v[68:71], v[8:11], v[48:51], v[68:71]
	v_mfma_f32_16x16x32_bf16 v[72:75], v[16:19], v[48:51], v[72:75]
	s_setprio 0
	s_waitcnt vmcnt(0)
	s_barrier
	v_mfma_f32_16x16x32_bf16 v[76:79], v[8:11], v[40:43], v[76:79]
	v_mfma_f32_16x16x32_bf16 v[80:83], v[16:19], v[40:43], v[80:83]
	s_mov_b32 m0, s45
	v_lshl_add_u64 v[2:3], s[40:41], 0, v[230:231]
	s_add_u32 s86, s40, 0x80000
	global_load_lds_dwordx4 v[2:3], off
	v_mfma_f32_16x16x32_bf16 v[84:87], v[8:11], v[32:35], v[84:87]
	v_lshl_add_u64 v[236:237], s[40:41], 0, v[228:229]
	s_mov_b32 m0, s48
	s_addc_u32 s87, s41, 0
	global_load_lds_dwordx4 v[236:237], off
	v_mfma_f32_16x16x32_bf16 v[92:95], v[16:19], v[32:35], v[92:95]
	v_lshl_add_u64 v[54:55], s[86:87], 0, v[230:231]
	s_mov_b32 m0, s49
	v_lshl_add_u64 v[238:239], s[46:47], 0, v[230:231]
	v_lshl_add_u64 v[54:55], s[86:87], 0, v[228:229]
	s_mov_b32 m0, s50
	v_lshl_add_u64 v[240:241], s[46:47], 0, v[228:229]
	s_mov_b32 m0, s44
	s_and_b64 vcc, exec, s[4:5]
	global_load_lds_dwordx4 v[238:239], off
	v_mfma_f32_16x16x32_bf16 v[96:99], v[8:11], v[24:27], v[96:99]
	s_mov_b32 m0, s51
	s_nop 0
	global_load_lds_dwordx4 v[240:241], off
	v_mfma_f32_16x16x32_bf16 v[100:103], v[16:19], v[24:27], v[100:103]
	s_barrier
	v_add_u32_e32 v1, 0x18000, v246
	ds_read_b128 v[4:7], v1
	ds_read_b128 v[8:11], v1 offset:1024
	ds_read_b128 v[12:15], v1 offset:2048
	ds_read_b128 v[16:19], v1 offset:3072
	v_add_u32_e32 v1, 0x1c000, v246
	s_add_u32 s46, s46, 0x80000
	s_addc_u32 s47, s47, 0
	s_mov_b32 m0, s56
	v_lshl_add_u64 v[112:113], s[46:47], 0, v[230:231]
	ds_read_b128 v[44:47], v249 offset:32768
	ds_read_b128 v[48:51], v249 offset:33792
	ds_read_b128 v[36:39], v249 offset:34816
	ds_read_b128 v[40:43], v249 offset:35840
	ds_read_b128 v[28:31], v249 offset:36864
	ds_read_b128 v[32:35], v249 offset:37888
	ds_read_b128 v[20:23], v249 offset:38912
	ds_read_b128 v[24:27], v249 offset:39936
	v_lshl_add_u64 v[112:113], s[46:47], 0, v[228:229]
	s_mov_b32 m0, s57
	s_nop 0
	s_setprio 1
	v_mfma_f32_16x16x32_bf16 v[68:71], v[180:183], v[220:223], v[68:71]
	v_mfma_f32_16x16x32_bf16 v[160:163], v[184:187], v[224:227], v[68:71]
	v_mfma_f32_16x16x32_bf16 v[68:71], v[188:191], v[220:223], v[72:75]
	v_mfma_f32_16x16x32_bf16 v[156:159], v[192:195], v[224:227], v[68:71]
	s_setprio 0
	s_barrier
	s_and_b64 vcc, exec, s[4:5]
	s_setprio 1
	v_mfma_f32_16x16x32_bf16 v[68:71], v[180:183], v[212:215], v[76:79]
	v_mfma_f32_16x16x32_bf16 v[152:155], v[184:187], v[216:219], v[68:71]
	v_mfma_f32_16x16x32_bf16 v[68:71], v[188:191], v[212:215], v[80:83]
	v_mfma_f32_16x16x32_bf16 v[148:151], v[192:195], v[216:219], v[68:71]
	s_setprio 0
	s_waitcnt lgkmcnt(0)
	s_barrier
	s_setprio 1
	v_mfma_f32_16x16x32_bf16 v[68:71], v[180:183], v[204:207], v[84:87]
	v_mfma_f32_16x16x32_bf16 v[136:139], v[184:187], v[208:211], v[68:71]
	s_setprio 0
	s_waitcnt vmcnt(0)
	s_barrier
	v_mfma_f32_16x16x32_bf16 v[68:71], v[188:191], v[204:207], v[92:95]
	v_mfma_f32_16x16x32_bf16 v[132:135], v[192:195], v[208:211], v[68:71]
	s_mov_b32 m0, s61
	v_lshl_add_u64 v[2:3], v[2:3], 0, s[14:15]
	s_add_u32 s40, s40, 0x80080
	global_load_lds_dwordx4 v[2:3], off
	v_mfma_f32_16x16x32_bf16 v[68:71], v[180:183], v[196:199], v[96:99]
	v_lshl_add_u64 v[2:3], v[236:237], 0, s[14:15]
	s_mov_b32 m0, s62
	s_addc_u32 s41, s41, 0
	global_load_lds_dwordx4 v[2:3], off
	v_mfma_f32_16x16x32_bf16 v[120:123], v[184:187], v[200:203], v[68:71]
	v_lshl_add_u64 v[2:3], s[40:41], 0, v[230:231]
	s_mov_b32 m0, s65
	s_and_b64 vcc, exec, s[4:5]
	v_lshl_add_u64 v[2:3], s[40:41], 0, v[228:229]
	s_mov_b32 m0, s66
	s_nop 0
	v_lshl_add_u64 v[2:3], v[238:239], 0, s[14:15]
	s_mov_b32 m0, s63
	s_nop 0
	global_load_lds_dwordx4 v[2:3], off
	v_mfma_f32_16x16x32_bf16 v[68:71], v[188:191], v[196:199], v[100:103]
	v_lshl_add_u64 v[2:3], v[240:241], 0, s[14:15]
	s_mov_b32 m0, s64
	s_nop 0
	global_load_lds_dwordx4 v[2:3], off
	v_mfma_f32_16x16x32_bf16 v[112:115], v[192:195], v[200:203], v[68:71]
	s_branch .Lq6_be
